# work queue: next ticket's atomic issued at the start of the current item's epilogue (q / kv / MLA / NSA items)
# baseline (speedup 1.0000x reference)
; DEVI void store_bf4(bf16_t* p, f32x4 v) { u32x2 w; w.x = pk2(v[0], v[1]); w.y = pk2(v[2], v[3]); *(u32x2*)p = w; }
; DEVI int opaque_tid(int wv) { int t; asm volatile("v_mbcnt_lo_u32_b32 %0, -1, 0\n\tv_mbcnt_hi_u32_b32 %0, -1, %0" : "=v"(t)); return wv * 64 + t; }
; template <int M> DEVI float shx(float v) { return __int_as_float(__builtin_amdgcn_ds_swizzle(__float_as_int(v), (M << 10) | 0x1f)); }
; template <bool ROWSS, class AD, class Epi>
; DEVI void gemm_tile(const AD& ad, const bf16_t* __restrict__ Bt, int K, int m0, int n0, const Epi& epi, unsigned char* lds, int wv) {
;     ...
;   float rs[4] = {1.f, 1.f, 1.f, 1.f};
;   if (ROWSS) {
;     float* rsl = (float*)(lds + LDS_RS_OFF);
; #pragma unroll
;     for (int i = 0; i < 4; ++i) {
;       float v = ss[i]; v += shx<1>(v); v += shx<2>(v); v += shx<4>(v);
;       if (lc == 0) rsl[lr + 64 * i] = rsqrtf(v / (float)K + 1e-6f);
;     }
;     __syncthreads();
; #pragma unroll
;     for (int i = 0; i < 4; ++i) rs[i] = rsl[wm * 64 + i * 16 + idx];
;   }
; #pragma unroll
;   for (int j = 0; j < 4; ++j) {
;     const int n = n0 + wn * 64 + j * 16 + quad * 4;
; #pragma unroll
;     for (int i = 0; i < 4; ++i) epi(m0 + wm * 64 + i * 16 + idx, n, acc[i][j], rs[i]);
;   DEVI void operator()(int m, int n, f32x4 v, float rs) const {
;     if (n >= 480) return;
;     v *= rs;
;     int d = n % 96;
;     if (d >= 64) {
;       const float4 cs = *(const float4*)(rope + ((size_t)m * 56 + 8 + ((d - 64) >> 1)) * 2);
;       float a0 = v[0] * cs.x - v[1] * cs.y, a1 = v[1] * cs.x + v[0] * cs.y;
;       float a2 = v[2] * cs.z - v[3] * cs.w, a3 = v[3] * cs.z + v[2] * cs.w;
;       v = (f32x4){a0, a1, a2, a3};
;     }
;     v *= QSCALE_MLA;
;     store_bf4(qm + (size_t)m * 512 + n, v);
; DEVI int next_item(unsigned* ctr, int* slot, int wv) {
;   __syncthreads();
;   if (opaque_tid(wv) == 0) *slot = (int)atomicAdd(ctr, 1u);
;   __syncthreads();
;   return *slot;
; }
.LBB0_864:
	s_or_b64 exec, exec, s[0:1]
	v_lshl_add_u32 v32, v112, 2, 0
	v_add_u32_e32 v32, 0x1b000, v32
	s_waitcnt lgkmcnt(0)
	s_barrier
	v_writelane_b32 v255, s0, 44
	v_writelane_b32 v255, s1, 45
	v_writelane_b32 v255, s2, 46
	v_writelane_b32 v255, s3, 47
	v_mbcnt_lo_u32_b32 v201, -1, 0
	v_mbcnt_hi_u32_b32 v201, -1, v201
	v_readlane_b32 s0, v252, 46
	s_nop 1
	v_add_u32_e32 v201, s0, v201
	v_cmp_eq_u32_e64 s[2:3], 0, v201
	s_nop 1
	s_and_saveexec_b64 s[0:1], s[2:3]
	s_cbranch_execz .Lpfq_skip
	v_readlane_b32 s2, v255, 21
	v_readlane_b32 s3, v255, 22
	v_mov_b32_e32 v200, 1
	s_nop 4
	global_atomic_add v200, v33, v200, s[2:3] sc0
.Lpfq_skip:
	s_mov_b64 exec, s[0:1]
	v_readlane_b32 s0, v255, 44
	v_readlane_b32 s1, v255, 45
	v_readlane_b32 s2, v255, 46
	v_readlane_b32 s3, v255, 47
	s_waitcnt vmcnt(3)
	ds_read2_b32 v[66:67], v32 offset1:16
	ds_read2_b32 v[60:61], v32 offset0:32 offset1:48
	v_lshlrev_b32_e32 v32, 2, v109
	s_waitcnt vmcnt(0)
	v_or3_b32 v78, v32, s3, v110
	v_or_b32_e32 v32, s2, v108
	s_mov_b32 s0, 0x2aaaaab
	v_add_u32_e32 v64, v111, v32
	v_mul_hi_u32 v32, v78, s0
	v_mul_u32_u24_e32 v32, 0x60, v32
	v_sub_u32_e32 v32, v78, v32
	v_cmp_lt_u32_e32 vcc, 63, v32
	v_subrev_u32_e32 v32, 64, v32
	v_lshrrev_b32_e32 v32, 1, v32
	s_waitcnt lgkmcnt(1)
	v_mov_b32_e32 v62, v67
	s_waitcnt lgkmcnt(0)
	v_mov_b32_e32 v58, v61
	v_add_u32_e32 v32, 8, v32
	v_pk_mul_f32 v[70:71], v[88:89], v[66:67] op_sel_hi:[1,0]
	v_pk_mul_f32 v[68:69], v[86:87], v[66:67] op_sel_hi:[1,0]
	v_ashrrev_i32_e32 v65, 31, v64
	s_and_saveexec_b64 s[0:1], vcc
	s_cbranch_execz .LBB0_866
	v_mad_i64_i32 v[72:73], s[2:3], v64, 56, v[32:33]
	v_readlane_b32 s2, v252, 63
	v_readlane_b32 s3, v253, 0
	s_nop 1
	v_lshl_add_u64 v[72:73], v[72:73], 3, s[2:3]
	global_load_dwordx4 v[72:75], v[72:73], off
	s_waitcnt vmcnt(0)
	v_pk_mul_f32 v[80:81], v[68:69], v[72:73] op_sel:[1,1] op_sel_hi:[0,1]
	v_pk_mul_f32 v[76:77], v[68:69], v[72:73] op_sel_hi:[1,0]
	v_pk_fma_f32 v[68:69], v[68:69], v[72:73], v[80:81] op_sel_hi:[1,0,1]
	s_nop 0
	v_mul_f32_e32 v68, v71, v75
	v_pk_fma_f32 v[72:73], v[70:71], v[74:75], v[68:69] op_sel_hi:[1,1,0] neg_lo:[0,0,1] neg_hi:[0,0,1]
	v_mul_f32_e32 v68, v70, v75
	v_pk_fma_f32 v[74:75], v[70:71], v[74:75], v[68:69] op_sel:[1,0,0] op_sel_hi:[0,1,0]
	v_sub_f32_e32 v68, v76, v80
	v_mov_b32_e32 v70, v72
	v_mov_b32_e32 v71, v74

; DEVI int opaque_tid(int wv) { int t; asm volatile("v_mbcnt_lo_u32_b32 %0, -1, 0\n\tv_mbcnt_hi_u32_b32 %0, -1, %0" : "=v"(t)); return wv * 64 + t; }
; DEVI int next_item(unsigned* ctr, int* slot, int wv) {
;   __syncthreads();
;   if (opaque_tid(wv) == 0) *slot = (int)atomicAdd(ctr, 1u);
;   __syncthreads();
;   return *slot;
; }
.LBB0_900:
	s_or_b64 exec, exec, s[0:1]
	v_readlane_b32 s0, v253, 48
	s_barrier
	v_mbcnt_lo_u32_b32 v0, -1, 0
	v_mbcnt_hi_u32_b32 v0, -1, v0
	s_nop 0
	v_cmp_eq_u32_e32 vcc, s0, v0
	s_and_saveexec_b64 s[0:1], vcc
	s_cbranch_execz .LBB0_849
	s_mov_b64 s[10:11], exec
	v_mbcnt_lo_u32_b32 v0, s10, 0
	v_mbcnt_hi_u32_b32 v0, s11, v0
	v_cmp_eq_u32_e32 vcc, 0, v0
	s_and_saveexec_b64 s[6:7], vcc
	s_cbranch_execz .LBB0_848
	s_waitcnt vmcnt(0)
	v_mov_b32_e32 v1, v200
	s_branch .LBB0_848

; DEVI bf16_t f2bf(float f) { return (bf16_t)(pk2(f, 0.f) & 0xffffu); }
; DEVI void store_bf4(bf16_t* p, f32x4 v) { u32x2 w; w.x = pk2(v[0], v[1]); w.y = pk2(v[2], v[3]); *(u32x2*)p = w; }
; DEVI int opaque_tid(int wv) { int t; asm volatile("v_mbcnt_lo_u32_b32 %0, -1, 0\n\tv_mbcnt_hi_u32_b32 %0, -1, %0" : "=v"(t)); return wv * 64 + t; }
;   DEVI void operator()(int m, int n, f32x4 v, float rs) const {
;     v *= rs;
;     if (n < 320) { store_bf4(kn + (size_t)m * 320 + n, v); }
;     else {
;       const int b = m >> 11, s = m & 2047; int e = n - 320;
;       bf16_t* dst = mlavT + ((size_t)((b * 5 + (e >> 6)) * 64 + (e & 63))) * S + s;
; #pragma unroll
;       for (int j = 0; j < 4; ++j) dst[(size_t)j * S] = f2bf(v[j]);
;     }
;   }
; DEVI int next_item(unsigned* ctr, int* slot, int wv) {
;   __syncthreads();
;   if (opaque_tid(wv) == 0) *slot = (int)atomicAdd(ctr, 1u);
;   __syncthreads();
;   return *slot;
; }
.LBB0_921:
	s_or_b64 exec, exec, s[0:1]
	v_lshl_add_u32 v32, v111, 2, 0
	v_add_u32_e32 v32, 0x1b000, v32
	s_waitcnt lgkmcnt(0)
	s_barrier
	v_writelane_b32 v255, s0, 44
	v_writelane_b32 v255, s1, 45
	v_writelane_b32 v255, s2, 46
	v_writelane_b32 v255, s3, 47
	v_mbcnt_lo_u32_b32 v201, -1, 0
	v_mbcnt_hi_u32_b32 v201, -1, v201
	v_readlane_b32 s0, v252, 46
	s_nop 1
	v_add_u32_e32 v201, s0, v201
	v_cmp_eq_u32_e64 s[2:3], 0, v201
	s_nop 1
	s_and_saveexec_b64 s[0:1], s[2:3]
	s_cbranch_execz .Lpfkv_skip
	v_readlane_b32 s2, v255, 21
	v_readlane_b32 s3, v255, 22
	v_mov_b32_e32 v200, 1
	s_nop 4
	global_atomic_add v200, v33, v200, s[2:3] sc0
.Lpfkv_skip:
	s_mov_b64 exec, s[0:1]
	v_readlane_b32 s0, v255, 44
	v_readlane_b32 s1, v255, 45
	v_readlane_b32 s2, v255, 46
	v_readlane_b32 s3, v255, 47
	s_waitcnt vmcnt(3)
	ds_read2_b32 v[68:69], v32 offset1:16
	ds_read2_b32 v[60:61], v32 offset0:32 offset1:48
	v_lshlrev_b32_e32 v59, 2, v108
	v_or_b32_e32 v32, s2, v107
	v_or3_b32 v64, v109, s3, v59
	s_waitcnt vmcnt(1)
	v_add_u32_e32 v76, v110, v32
	s_movk_i32 s0, 0x13f
	v_add_u32_e32 v32, 0xfffffec0, v64
	s_waitcnt vmcnt(0)
	v_ashrrev_i32_e32 v78, 11, v76
	v_and_b32_e32 v63, 0x7cf, v76
	s_waitcnt lgkmcnt(1)
	v_mov_b32_e32 v62, v69
	s_waitcnt lgkmcnt(0)
	v_mov_b32_e32 v58, v61
	v_cmp_lt_i32_e64 s[0:1], s0, v64
	v_pk_mul_f32 v[66:67], v[88:89], v[68:69] op_sel_hi:[1,0]
	v_pk_mul_f32 v[72:73], v[86:87], v[68:69] op_sel_hi:[1,0]
	v_mad_i32_i24 v61, v78, s70, v32
	v_lshlrev_b32_e32 v32, 1, v63
	s_and_saveexec_b64 s[2:3], s[0:1]
	s_xor_b64 s[6:7], exec, s[2:3]
	s_cbranch_execz .LBB0_923
	v_and_or_b32 v70, v61, s74, v59
	v_ashrrev_i32_e32 v71, 31, v70
	v_readlane_b32 s2, v253, 32
	v_lshlrev_b64 v[70:71], 12, v[70:71]
	v_readlane_b32 s3, v253, 33
	v_cvt_pk_bf16_f32 v63, v72, v33
	s_nop 1
	v_lshl_add_u64 v[70:71], s[2:3], 0, v[70:71]
	v_lshl_add_u64 v[70:71], v[70:71], 0, v[32:33]
	v_add_co_u32_e32 v72, vcc, 0x1000, v70
	global_store_short v[70:71], v63, off
	v_cvt_pk_bf16_f32 v63, v73, v33
	s_nop 0
	v_addc_co_u32_e32 v73, vcc, 0, v71, vcc
	global_store_short v[72:73], v63, off
	v_add_co_u32_e32 v72, vcc, 0x2000, v70
	v_cvt_pk_bf16_f32 v63, v66, v33
	s_nop 1
	v_addc_co_u32_e32 v73, vcc, 0, v71, vcc
	v_add_co_u32_e32 v66, vcc, 0x3000, v70
	global_store_short v[72:73], v63, off
	v_cvt_pk_bf16_f32 v63, v67, v33
	s_nop 0
	v_addc_co_u32_e32 v67, vcc, 0, v71, vcc
	global_store_short v[66:67], v63, off

; DEVI int opaque_tid(int wv) { int t; asm volatile("v_mbcnt_lo_u32_b32 %0, -1, 0\n\tv_mbcnt_hi_u32_b32 %0, -1, %0" : "=v"(t)); return wv * 64 + t; }
; DEVI int next_item(unsigned* ctr, int* slot, int wv) {
;   __syncthreads();
;   if (opaque_tid(wv) == 0) *slot = (int)atomicAdd(ctr, 1u);
;   __syncthreads();
;   return *slot;
; }
.LBB0_985:
	s_or_b64 exec, exec, s[0:1]
	v_readlane_b32 s0, v253, 48
	s_waitcnt vmcnt(63) expcnt(7) lgkmcnt(15)
	s_barrier
	v_mbcnt_lo_u32_b32 v0, -1, 0
	v_mbcnt_hi_u32_b32 v0, -1, v0
	s_nop 0
	v_cmp_eq_u32_e32 vcc, s0, v0
	s_and_saveexec_b64 s[0:1], vcc
	s_cbranch_execz .LBB0_906
	s_mov_b64 s[10:11], exec
	v_mbcnt_lo_u32_b32 v0, s10, 0
	v_mbcnt_hi_u32_b32 v0, s11, v0
	v_cmp_eq_u32_e32 vcc, 0, v0
	s_and_saveexec_b64 s[6:7], vcc
	s_cbranch_execz .LBB0_905
	s_waitcnt vmcnt(0)
	v_mov_b32_e32 v1, v200
	s_branch .LBB0_905

; DEVI void store_bf4(bf16_t* p, f32x4 v) { u32x2 w; w.x = pk2(v[0], v[1]); w.y = pk2(v[2], v[3]); *(u32x2*)p = w; }
; DEVI int opaque_tid(int wv) { int t; asm volatile("v_mbcnt_lo_u32_b32 %0, -1, 0\n\tv_mbcnt_hi_u32_b32 %0, -1, %0" : "=v"(t)); return wv * 64 + t; }
; template <int M> DEVI float shx(float v) { return __int_as_float(__builtin_amdgcn_ds_swizzle(__float_as_int(v), (M << 10) | 0x1f)); }
; DEVI float shx32(float v, int lane) { return __int_as_float(__builtin_amdgcn_ds_bpermute((lane ^ 32) << 2, __float_as_int(v))); }
; DEVI void mla_item(const Ctx& cx, int b, int h, int qt, unsigned char* lds, int wv) {
;     ...
; #pragma unroll
;   for (int c = 0; c < 2; ++c) {
;     float lt = lrn[c]; lt += shx<16>(lt); lt += shx32(lt, quad * 16 + idx);
;     const float il = lt > 0.f ? 1.f / lt : 0.f;
; #pragma unroll
;     for (int d = 0; d < 4; ++d) store_bf4(cx.mixed + ((size_t)(b * S + tq[c])) * DM + 384 + h * 64 + d * 16 + quad * 4, o[c][d] * il);
;   }
; DEVI int next_item(unsigned* ctr, int* slot, int wv) {
;   __syncthreads();
;   if (opaque_tid(wv) == 0) *slot = (int)atomicAdd(ctr, 1u);
;   __syncthreads();
;   return *slot;
; }
.LBB0_1388:
	v_writelane_b32 v255, s0, 44
	v_writelane_b32 v255, s1, 45
	v_writelane_b32 v255, s2, 46
	v_writelane_b32 v255, s3, 47
	v_mbcnt_lo_u32_b32 v201, -1, 0
	v_mbcnt_hi_u32_b32 v201, -1, v201
	v_readlane_b32 s0, v252, 46
	s_nop 1
	v_add_u32_e32 v201, s0, v201
	v_cmp_eq_u32_e64 s[2:3], 0, v201
	s_nop 1
	s_and_saveexec_b64 s[0:1], s[2:3]
	s_cbranch_execz .Lpfmla_skip
	v_readlane_b32 s2, v255, 21
	v_readlane_b32 s3, v255, 22
	v_mov_b32_e32 v200, 1
	s_nop 4
	global_atomic_add v200, v33, v200, s[2:3] offset:4 sc0
.Lpfmla_skip:
	s_mov_b64 exec, s[0:1]
	v_readlane_b32 s0, v255, 44
	v_readlane_b32 s1, v255, 45
	v_readlane_b32 s2, v255, 46
	v_readlane_b32 s3, v255, 47
	ds_swizzle_b32 v0, v92 offset:swizzle(SWAP,16)
	v_readlane_b32 s4, v254, 14
	v_readlane_b32 s5, v254, 15
	v_lshlrev_b32_e32 v32, 1, v115
	s_waitcnt lgkmcnt(0)
	v_add_f32_e32 v2, v92, v0
	ds_bpermute_b32 v3, v110, v2
	v_lshlrev_b64 v[0:1], 11, v[88:89]
	v_lshl_add_u64 v[0:1], s[4:5], 0, v[0:1]
	v_lshl_add_u64 v[0:1], v[0:1], 0, s[6:7]
	v_lshl_add_u64 v[0:1], v[0:1], 0, v[32:33]
	s_waitcnt lgkmcnt(0)
	v_add_f32_e32 v2, v2, v3
	v_div_scale_f32 v3, s[0:1], v2, v2, 1.0
	v_rcp_f32_e32 v4, v3
	v_div_scale_f32 v5, vcc, 1.0, v2, 1.0
	v_fma_f32 v6, -v3, v4, 1.0
	v_fmac_f32_e32 v4, v6, v4
	v_mul_f32_e32 v6, v5, v4
	v_fma_f32 v7, -v3, v6, v5
	v_fmac_f32_e32 v6, v7, v4
	v_fma_f32 v3, -v3, v6, v5
	v_div_fmas_f32 v3, v3, v4, v6
	v_div_fixup_f32 v3, v3, v2, 1.0
	v_cmp_lt_f32_e32 vcc, 0, v2
	s_nop 1
	v_cndmask_b32_e32 v2, 0, v3, vcc
	v_pk_mul_f32 v[6:7], v[66:67], v[2:3] op_sel_hi:[1,0]
	v_pk_mul_f32 v[4:5], v[68:69], v[2:3] op_sel_hi:[1,0]
	v_cvt_pk_bf16_f32 v6, v6, v7
	s_nop 0
	v_cvt_pk_bf16_f32 v7, v4, v5
	global_store_dwordx2 v[0:1], v[6:7], off offset:768
	v_pk_mul_f32 v[4:5], v[64:65], v[2:3] op_sel_hi:[1,0]
	v_pk_mul_f32 v[6:7], v[62:63], v[2:3] op_sel_hi:[1,0]
	ds_swizzle_b32 v3, v93 offset:swizzle(SWAP,16)
	v_cvt_pk_bf16_f32 v6, v6, v7
	v_cvt_pk_bf16_f32 v7, v4, v5
	global_store_dwordx2 v[0:1], v[6:7], off offset:800
	s_waitcnt lgkmcnt(0)
	v_add_f32_e32 v8, v93, v3
	ds_bpermute_b32 v9, v110, v8
	v_pk_mul_f32 v[6:7], v[58:59], v[2:3] op_sel_hi:[1,0]
	v_pk_mul_f32 v[4:5], v[60:61], v[2:3] op_sel_hi:[1,0]
	v_cvt_pk_bf16_f32 v6, v6, v7
	s_nop 0
	v_cvt_pk_bf16_f32 v7, v4, v5
	global_store_dwordx2 v[0:1], v[6:7], off offset:832
	s_waitcnt lgkmcnt(0)
	v_add_f32_e32 v6, v8, v9
	v_div_scale_f32 v7, s[0:1], v6, v6, 1.0
	v_rcp_f32_e32 v8, v7
	v_pk_mul_f32 v[4:5], v[56:57], v[2:3] op_sel_hi:[1,0]
	v_pk_mul_f32 v[2:3], v[54:55], v[2:3] op_sel_hi:[1,0]
	v_readlane_b32 s0, v253, 48
	v_cvt_pk_bf16_f32 v2, v2, v3
	v_cvt_pk_bf16_f32 v3, v4, v5
	global_store_dwordx2 v[0:1], v[2:3], off offset:864
	v_fma_f32 v0, -v7, v8, 1.0
	v_fmac_f32_e32 v8, v0, v8
	v_div_scale_f32 v0, vcc, 1.0, v6, 1.0
	v_mul_f32_e32 v1, v0, v8
	v_fma_f32 v2, -v7, v1, v0
	v_fmac_f32_e32 v1, v2, v8
	v_fma_f32 v0, -v7, v1, v0
	v_div_fmas_f32 v0, v0, v8, v1
	v_div_fixup_f32 v0, v0, v6, 1.0
	v_cmp_lt_f32_e32 vcc, 0, v6
	v_lshlrev_b64 v[2:3], 11, v[86:87]
	v_lshl_add_u64 v[2:3], s[4:5], 0, v[2:3]
	v_cndmask_b32_e32 v0, 0, v0, vcc
	v_lshl_add_u64 v[2:3], v[2:3], 0, s[6:7]
	v_pk_mul_f32 v[6:7], v[50:51], v[0:1] op_sel_hi:[1,0]
	v_lshl_add_u64 v[2:3], v[2:3], 0, v[32:33]
	v_pk_mul_f32 v[4:5], v[52:53], v[0:1] op_sel_hi:[1,0]
	v_cvt_pk_bf16_f32 v6, v6, v7
	s_nop 0
	v_cvt_pk_bf16_f32 v7, v4, v5
	global_store_dwordx2 v[2:3], v[6:7], off offset:768
	v_pk_mul_f32 v[6:7], v[46:47], v[0:1] op_sel_hi:[1,0]
	v_pk_mul_f32 v[4:5], v[48:49], v[0:1] op_sel_hi:[1,0]
	v_cvt_pk_bf16_f32 v6, v6, v7
	s_nop 0
	v_cvt_pk_bf16_f32 v7, v4, v5
	global_store_dwordx2 v[2:3], v[6:7], off offset:800
	v_pk_mul_f32 v[4:5], v[44:45], v[0:1] op_sel_hi:[1,0]
	v_pk_mul_f32 v[6:7], v[42:43], v[0:1] op_sel_hi:[1,0]
	s_nop 0
	v_cvt_pk_bf16_f32 v6, v6, v7
	v_cvt_pk_bf16_f32 v7, v4, v5
	v_pk_mul_f32 v[4:5], v[40:41], v[0:1] op_sel_hi:[1,0]
	v_pk_mul_f32 v[0:1], v[38:39], v[0:1] op_sel_hi:[1,0]
	global_store_dwordx2 v[2:3], v[6:7], off offset:832
	v_cvt_pk_bf16_f32 v0, v0, v1
	v_cvt_pk_bf16_f32 v1, v4, v5
	global_store_dwordx2 v[2:3], v[0:1], off offset:864
	s_barrier
	v_mbcnt_lo_u32_b32 v0, -1, 0
	v_mbcnt_hi_u32_b32 v0, -1, v0
	s_nop 0
	v_cmp_eq_u32_e32 vcc, s0, v0
	s_and_saveexec_b64 s[0:1], vcc
	s_cbranch_execz .LBB0_1353
	s_mov_b64 s[6:7], exec
	v_mbcnt_lo_u32_b32 v0, s6, 0
	v_mbcnt_hi_u32_b32 v0, s7, v0
	v_cmp_eq_u32_e32 vcc, 0, v0
	s_and_saveexec_b64 s[4:5], vcc
	s_cbranch_execz .LBB0_1352
	s_waitcnt vmcnt(0)
	v_mov_b32_e32 v1, v200
	s_branch .LBB0_1352

; DEVI float bf2f(bf16_t b) { return __uint_as_float(((unsigned)b) << 16); }
; DEVI void store_bf4(bf16_t* p, f32x4 v) { u32x2 w; w.x = pk2(v[0], v[1]); w.y = pk2(v[2], v[3]); *(u32x2*)p = w; }
; DEVI float sigmoidf(float x) { return 1.f / (1.f + __expf(-x)); }
; template <int M> DEVI float shx(float v) { return __int_as_float(__builtin_amdgcn_ds_swizzle(__float_as_int(v), (M << 10) | 0x1f)); }
; DEVI float shx32(float v, int lane) { return __int_as_float(__builtin_amdgcn_ds_bpermute((lane ^ 32) << 2, __float_as_int(v))); }
; DEVI void nsa_item(const Ctx& cx, const unsigned* cflag, int b, int g, int qt, unsigned char* lds, int wv) {
;     ...
;   {
;     const bf16_t* gp = proj + (size_t)(tokrow * (unsigned)PS + (unsigned)(C_GATE + g * 9));
; #pragma unroll
;     for (int c = 0; c < 3; ++c) {
;       float lt = lrn[c]; lt += shx<16>(lt); lt += shx32(lt, quad * 16 + idx);
;       const float gt = sigmoidf(bf2f(gp[c * 3 + 2])) * (lt > 0.f ? 1.f / lt : 0.f);
; #pragma unroll
;       for (int d = 0; d < 4; ++d) store_bf4(cx.mixed + (size_t)(tokrow * (unsigned)DM + (unsigned)((g * 3 + c) * 64 + d * 16 + quad * 4)), scr[c * 4 + d] + o[c][d] * gt);
;     }
;   }
.Lpfnsa_skip:
	s_mov_b64 exec, s[0:1]
	v_readlane_b32 s0, v255, 44
	v_readlane_b32 s1, v255, 45
	v_readlane_b32 s2, v255, 46
	v_readlane_b32 s3, v255, 47
	global_load_ushort v6, v[110:111], off offset:4
	global_load_dwordx4 v[0:3], v[108:109], off
	s_waitcnt vmcnt(6)
	ds_swizzle_b32 v4, v148 offset:swizzle(SWAP,16)
	v_lshl_or_b32 v7, v123, 10, v127
	v_readlane_b32 s4, v254, 14
	v_or_b32_e32 v32, s96, v7
	v_readlane_b32 s5, v254, 15
	s_waitcnt lgkmcnt(0)
	v_add_f32_e32 v4, v148, v4
	ds_bpermute_b32 v5, v122, v4
	s_waitcnt vmcnt(5) lgkmcnt(0)
	v_add_f32_e32 v8, v4, v5
	v_div_scale_f32 v9, s[0:1], v8, v8, 1.0
	v_rcp_f32_e32 v10, v9
	v_div_scale_f32 v11, s[0:1], 1.0, v8, 1.0
	v_lshl_add_u64 v[4:5], v[32:33], 1, s[4:5]
	s_waitcnt vmcnt(4)
	v_fma_f32 v12, -v9, v10, 1.0
	v_fmac_f32_e32 v10, v12, v10
	v_mul_f32_e32 v12, v11, v10
	v_fma_f32 v13, -v9, v12, v11
	v_fmac_f32_e32 v12, v13, v10
	v_fma_f32 v9, -v9, v12, v11
	s_waitcnt vmcnt(1)
	v_lshlrev_b32_e32 v6, 16, v6
	v_mul_f32_e32 v6, 0xbfb8aa3b, v6
	v_exp_f32_e32 v6, v6
	s_nop 0
	v_add_f32_e32 v6, 1.0, v6
	v_div_scale_f32 v13, s[2:3], v6, v6, 1.0
	v_rcp_f32_e32 v14, v13
	v_div_scale_f32 v11, vcc, 1.0, v6, 1.0
	v_fma_f32 v15, -v13, v14, 1.0
	v_fmac_f32_e32 v14, v15, v14
	v_mul_f32_e32 v15, v11, v14
	v_fma_f32 v16, -v13, v15, v11
	v_fmac_f32_e32 v15, v16, v14
	v_fma_f32 v11, -v13, v15, v11
	v_div_fmas_f32 v11, v11, v14, v15
	s_mov_b64 vcc, s[0:1]
	v_div_fmas_f32 v9, v9, v10, v12
	v_div_fixup_f32 v9, v9, v8, 1.0
	v_cmp_lt_f32_e32 vcc, 0, v8
	v_div_fixup_f32 v6, v11, v6, 1.0
	s_add_i32 s0, s96, 64
	v_cndmask_b32_e32 v8, 0, v9, vcc
	v_mul_f32_e32 v6, v8, v6
	s_waitcnt vmcnt(0)
	v_pk_fma_f32 v[0:1], v[80:81], v[6:7], v[0:1] op_sel_hi:[1,0,1]
	v_pk_fma_f32 v[2:3], v[82:83], v[6:7], v[2:3] op_sel_hi:[1,0,1]
	v_cvt_pk_bf16_f32 v0, v0, v1
	s_addk_i32 s96, 0x80
	v_cvt_pk_bf16_f32 v1, v2, v3
	global_store_dwordx2 v[4:5], v[0:1], off
	global_load_dwordx4 v[0:3], v[108:109], off offset:16
	v_mov_b32_e32 v5, v33
	v_or_b32_e32 v4, 16, v32
	v_lshl_add_u64 v[4:5], v[4:5], 1, s[4:5]
	s_waitcnt vmcnt(0)
	v_pk_fma_f32 v[0:1], v[76:77], v[6:7], v[0:1] op_sel_hi:[1,0,1]
	v_pk_fma_f32 v[2:3], v[78:79], v[6:7], v[2:3] op_sel_hi:[1,0,1]
	v_cvt_pk_bf16_f32 v0, v0, v1
	s_nop 0
	v_cvt_pk_bf16_f32 v1, v2, v3
	global_store_dwordx2 v[4:5], v[0:1], off
	global_load_dwordx4 v[0:3], v[108:109], off offset:32
	v_mov_b32_e32 v5, v33
	v_or_b32_e32 v4, 32, v32
	v_lshl_add_u64 v[4:5], v[4:5], 1, s[4:5]
	v_or_b32_e32 v32, 48, v32
	s_waitcnt vmcnt(0)
	v_pk_fma_f32 v[0:1], v[72:73], v[6:7], v[0:1] op_sel_hi:[1,0,1]
	v_pk_fma_f32 v[2:3], v[74:75], v[6:7], v[2:3] op_sel_hi:[1,0,1]
	v_cvt_pk_bf16_f32 v0, v0, v1
	s_nop 0
	v_cvt_pk_bf16_f32 v1, v2, v3
	global_store_dwordx2 v[4:5], v[0:1], off
	global_load_dwordx4 v[0:3], v[108:109], off offset:48
	v_lshl_add_u64 v[4:5], v[32:33], 1, s[4:5]
	v_or_b32_e32 v32, s0, v7
	s_waitcnt vmcnt(0)
	v_pk_fma_f32 v[0:1], v[68:69], v[6:7], v[0:1] op_sel_hi:[1,0,1]
	v_pk_fma_f32 v[2:3], v[70:71], v[6:7], v[2:3] op_sel_hi:[1,0,1]
	v_cvt_pk_bf16_f32 v0, v0, v1
	s_nop 0
	v_cvt_pk_bf16_f32 v1, v2, v3
	global_store_dwordx2 v[4:5], v[0:1], off
	global_load_ushort v6, v[110:111], off offset:10
	s_nop 0
	global_load_dwordx4 v[0:3], v[108:109], off offset:64
	ds_swizzle_b32 v4, v117 offset:swizzle(SWAP,16)
	s_waitcnt lgkmcnt(0)
	v_add_f32_e32 v4, v117, v4
	ds_bpermute_b32 v5, v122, v4
	s_waitcnt lgkmcnt(0)
	v_add_f32_e32 v8, v4, v5
	v_div_scale_f32 v9, s[0:1], v8, v8, 1.0
	v_rcp_f32_e32 v10, v9
	v_div_scale_f32 v11, s[0:1], 1.0, v8, 1.0
	v_lshl_add_u64 v[4:5], v[32:33], 1, s[4:5]
	v_fma_f32 v12, -v9, v10, 1.0
	v_fmac_f32_e32 v10, v12, v10
	v_mul_f32_e32 v12, v11, v10
	v_fma_f32 v13, -v9, v12, v11
	v_fmac_f32_e32 v12, v13, v10
	v_fma_f32 v9, -v9, v12, v11
	s_waitcnt vmcnt(1)
	v_lshlrev_b32_e32 v6, 16, v6
	v_mul_f32_e32 v6, 0xbfb8aa3b, v6
	v_exp_f32_e32 v6, v6
	s_nop 0
	v_add_f32_e32 v6, 1.0, v6
	v_div_scale_f32 v13, s[2:3], v6, v6, 1.0
	v_rcp_f32_e32 v14, v13
	v_div_scale_f32 v11, vcc, 1.0, v6, 1.0
	v_fma_f32 v15, -v13, v14, 1.0
	v_fmac_f32_e32 v14, v15, v14
	v_mul_f32_e32 v15, v11, v14
	v_fma_f32 v16, -v13, v15, v11
	v_fmac_f32_e32 v15, v16, v14
	v_fma_f32 v11, -v13, v15, v11
	v_div_fmas_f32 v11, v11, v14, v15
	s_mov_b64 vcc, s[0:1]
	v_div_fmas_f32 v9, v9, v10, v12
	v_div_fixup_f32 v9, v9, v8, 1.0
	v_cmp_lt_f32_e32 vcc, 0, v8
	v_div_fixup_f32 v6, v11, v6, 1.0
	s_nop 0
	v_cndmask_b32_e32 v8, 0, v9, vcc
	v_mul_f32_e32 v6, v8, v6
	s_waitcnt vmcnt(0)
; DEVI float bf2f(bf16_t b) { return __uint_as_float(((unsigned)b) << 16); }
; DEVI void store_bf4(bf16_t* p, f32x4 v) { u32x2 w; w.x = pk2(v[0], v[1]); w.y = pk2(v[2], v[3]); *(u32x2*)p = w; }
; DEVI float sigmoidf(float x) { return 1.f / (1.f + __expf(-x)); }
; DEVI int opaque_tid(int wv) { int t; asm volatile("v_mbcnt_lo_u32_b32 %0, -1, 0\n\tv_mbcnt_hi_u32_b32 %0, -1, %0" : "=v"(t)); return wv * 64 + t; }
; template <int M> DEVI float shx(float v) { return __int_as_float(__builtin_amdgcn_ds_swizzle(__float_as_int(v), (M << 10) | 0x1f)); }
; DEVI float shx32(float v, int lane) { return __int_as_float(__builtin_amdgcn_ds_bpermute((lane ^ 32) << 2, __float_as_int(v))); }
; DEVI void nsa_item(const Ctx& cx, const unsigned* cflag, int b, int g, int qt, unsigned char* lds, int wv) {
;     ...
;   {
;     const bf16_t* gp = proj + (size_t)(tokrow * (unsigned)PS + (unsigned)(C_GATE + g * 9));
; #pragma unroll
;     for (int c = 0; c < 3; ++c) {
;       float lt = lrn[c]; lt += shx<16>(lt); lt += shx32(lt, quad * 16 + idx);
;       const float gt = sigmoidf(bf2f(gp[c * 3 + 2])) * (lt > 0.f ? 1.f / lt : 0.f);
; #pragma unroll
;       for (int d = 0; d < 4; ++d) store_bf4(cx.mixed + (size_t)(tokrow * (unsigned)DM + (unsigned)((g * 3 + c) * 64 + d * 16 + quad * 4)), scr[c * 4 + d] + o[c][d] * gt);
;     }
;   }
; DEVI int next_item(unsigned* ctr, int* slot, int wv) {
;   __syncthreads();
;   if (opaque_tid(wv) == 0) *slot = (int)atomicAdd(ctr, 1u);
;   __syncthreads();
;   return *slot;
; }
	v_pk_fma_f32 v[0:1], v[64:65], v[6:7], v[0:1] op_sel_hi:[1,0,1]
	v_pk_fma_f32 v[2:3], v[66:67], v[6:7], v[2:3] op_sel_hi:[1,0,1]
	v_cvt_pk_bf16_f32 v0, v0, v1
	s_nop 0
	v_cvt_pk_bf16_f32 v1, v2, v3
	global_store_dwordx2 v[4:5], v[0:1], off
	global_load_dwordx4 v[0:3], v[108:109], off offset:80
	v_mov_b32_e32 v5, v33
	v_or_b32_e32 v4, 16, v32
	v_lshl_add_u64 v[4:5], v[4:5], 1, s[4:5]
	s_waitcnt vmcnt(0)
	v_pk_fma_f32 v[0:1], v[60:61], v[6:7], v[0:1] op_sel_hi:[1,0,1]
	v_pk_fma_f32 v[2:3], v[62:63], v[6:7], v[2:3] op_sel_hi:[1,0,1]
	v_cvt_pk_bf16_f32 v0, v0, v1
	s_nop 0
	v_cvt_pk_bf16_f32 v1, v2, v3
	global_store_dwordx2 v[4:5], v[0:1], off
	global_load_dwordx4 v[0:3], v[108:109], off offset:96
	v_mov_b32_e32 v5, v33
	v_or_b32_e32 v4, 32, v32
	v_lshl_add_u64 v[4:5], v[4:5], 1, s[4:5]
	v_or_b32_e32 v32, 48, v32
	s_waitcnt vmcnt(0)
	v_pk_fma_f32 v[0:1], v[56:57], v[6:7], v[0:1] op_sel_hi:[1,0,1]
	v_pk_fma_f32 v[2:3], v[58:59], v[6:7], v[2:3] op_sel_hi:[1,0,1]
	v_cvt_pk_bf16_f32 v0, v0, v1
	s_nop 0
	v_cvt_pk_bf16_f32 v1, v2, v3
	global_store_dwordx2 v[4:5], v[0:1], off
	global_load_dwordx4 v[0:3], v[108:109], off offset:112
	v_lshl_add_u64 v[4:5], v[32:33], 1, s[4:5]
	v_or_b32_e32 v32, s96, v7
	s_waitcnt vmcnt(0)
	v_pk_fma_f32 v[0:1], v[52:53], v[6:7], v[0:1] op_sel_hi:[1,0,1]
	v_pk_fma_f32 v[2:3], v[54:55], v[6:7], v[2:3] op_sel_hi:[1,0,1]
	v_cvt_pk_bf16_f32 v0, v0, v1
	s_nop 0
	v_cvt_pk_bf16_f32 v1, v2, v3
	global_store_dwordx2 v[4:5], v[0:1], off
	global_load_ushort v6, v[110:111], off offset:16
	s_nop 0
	global_load_dwordx4 v[0:3], v[108:109], off offset:128
	ds_swizzle_b32 v4, v116 offset:swizzle(SWAP,16)
	s_waitcnt lgkmcnt(0)
	v_add_f32_e32 v4, v116, v4
	ds_bpermute_b32 v5, v122, v4
	s_waitcnt lgkmcnt(0)
	v_add_f32_e32 v7, v4, v5
	v_div_scale_f32 v8, s[0:1], v7, v7, 1.0
	v_rcp_f32_e32 v9, v8
	v_div_scale_f32 v10, s[0:1], 1.0, v7, 1.0
	v_lshl_add_u64 v[4:5], v[32:33], 1, s[4:5]
	v_fma_f32 v11, -v8, v9, 1.0
	v_fmac_f32_e32 v9, v11, v9
	v_mul_f32_e32 v11, v10, v9
	v_fma_f32 v12, -v8, v11, v10
	v_fmac_f32_e32 v11, v12, v9
	v_fma_f32 v8, -v8, v11, v10
	s_waitcnt vmcnt(1)
	v_lshlrev_b32_e32 v6, 16, v6
	v_mul_f32_e32 v6, 0xbfb8aa3b, v6
	v_exp_f32_e32 v6, v6
	s_nop 0
	v_add_f32_e32 v6, 1.0, v6
	v_div_scale_f32 v12, s[2:3], v6, v6, 1.0
	v_rcp_f32_e32 v13, v12
	v_div_scale_f32 v10, vcc, 1.0, v6, 1.0
	v_fma_f32 v14, -v12, v13, 1.0
	v_fmac_f32_e32 v13, v14, v13
	v_mul_f32_e32 v14, v10, v13
	v_fma_f32 v15, -v12, v14, v10
	v_fmac_f32_e32 v14, v15, v13
	v_fma_f32 v10, -v12, v14, v10
	v_div_fmas_f32 v10, v10, v13, v14
	s_mov_b64 vcc, s[0:1]
	v_div_fmas_f32 v8, v8, v9, v11
	v_div_fixup_f32 v8, v8, v7, 1.0
	v_cmp_lt_f32_e32 vcc, 0, v7
	v_div_fixup_f32 v6, v10, v6, 1.0
	v_readlane_b32 s0, v253, 48
	v_cndmask_b32_e32 v7, 0, v8, vcc
	v_mul_f32_e32 v6, v7, v6
	s_waitcnt vmcnt(0)
	v_pk_fma_f32 v[0:1], v[48:49], v[6:7], v[0:1] op_sel_hi:[1,0,1]
	v_pk_fma_f32 v[2:3], v[50:51], v[6:7], v[2:3] op_sel_hi:[1,0,1]
	v_cvt_pk_bf16_f32 v0, v0, v1
	s_nop 0
	v_cvt_pk_bf16_f32 v1, v2, v3
	global_store_dwordx2 v[4:5], v[0:1], off
	global_load_dwordx4 v[0:3], v[108:109], off offset:144
	v_mov_b32_e32 v5, v33
	v_or_b32_e32 v4, 16, v32
	v_lshl_add_u64 v[4:5], v[4:5], 1, s[4:5]
	s_waitcnt vmcnt(0)
	v_pk_fma_f32 v[0:1], v[44:45], v[6:7], v[0:1] op_sel_hi:[1,0,1]
	v_pk_fma_f32 v[2:3], v[46:47], v[6:7], v[2:3] op_sel_hi:[1,0,1]
	v_cvt_pk_bf16_f32 v0, v0, v1
	s_nop 0
	v_cvt_pk_bf16_f32 v1, v2, v3
	global_store_dwordx2 v[4:5], v[0:1], off
	global_load_dwordx4 v[0:3], v[108:109], off offset:160
	v_mov_b32_e32 v5, v33
	v_or_b32_e32 v4, 32, v32
	v_lshl_add_u64 v[4:5], v[4:5], 1, s[4:5]
	v_or_b32_e32 v32, 48, v32
	s_waitcnt vmcnt(0)
	v_pk_fma_f32 v[0:1], v[40:41], v[6:7], v[0:1] op_sel_hi:[1,0,1]
	v_pk_fma_f32 v[2:3], v[42:43], v[6:7], v[2:3] op_sel_hi:[1,0,1]
	v_cvt_pk_bf16_f32 v0, v0, v1
	s_nop 0
	v_cvt_pk_bf16_f32 v1, v2, v3
	global_store_dwordx2 v[4:5], v[0:1], off
	global_load_dwordx4 v[0:3], v[108:109], off offset:176
	v_lshl_add_u64 v[4:5], v[32:33], 1, s[4:5]
	s_waitcnt vmcnt(0)
	v_pk_fma_f32 v[0:1], v[36:37], v[6:7], v[0:1] op_sel_hi:[1,0,1]
	s_nop 0
	v_cvt_pk_bf16_f32 v0, v0, v1
	v_pk_fma_f32 v[2:3], v[38:39], v[6:7], v[2:3] op_sel_hi:[1,0,1]
	s_nop 0
	v_cvt_pk_bf16_f32 v1, v2, v3
	global_store_dwordx2 v[4:5], v[0:1], off
	s_barrier
	v_mbcnt_lo_u32_b32 v0, -1, 0
	v_mbcnt_hi_u32_b32 v0, -1, v0
	s_nop 0
	v_cmp_eq_u32_e32 vcc, s0, v0
	s_and_saveexec_b64 s[0:1], vcc
	s_cbranch_execz .LBB0_1395
	s_mov_b64 s[6:7], exec
	v_mbcnt_lo_u32_b32 v0, s6, 0
	v_mbcnt_hi_u32_b32 v0, s7, v0
	v_cmp_eq_u32_e32 vcc, 0, v0
	s_and_saveexec_b64 s[4:5], vcc
	s_cbranch_execz .LBB0_1394
	s_waitcnt vmcnt(0)
	v_mov_b32_e32 v1, v200
	s_branch .LBB0_1394
